# merged GEMM: six gate quads of the second row half kept in free VGPRs across the next unit's K loop and reused as that unit's gate (same elements) - six fewer gate loads in units 1,2
# speedup vs baseline: 1.0050x; 1.0034x over previous
;     __device__ __forceinline__ void operator()(const acc_t& acc, const Unit& u, int wr, int wc, int fr, int fq) const { run(acc, u, wr, wc, fr, fq, 0, 2); }
;     __device__ __forceinline__ void operator()(const acc_t& acc, const Unit& u, int wr, int wc, int fr, int fq) const { run(acc, u, wr, wc, fr, fq, 0, 2); }
;     __device__ __forceinline__ void operator()(acc_t& acc, const Unit& u, int wr, int wc, int fr, int fq) const {
;         const int br = u.br; const size_t base = (size_t)(u.pm * BM + wr * 64 + fr) * D + u.pn * BM + wc * 32 + 8 * fq;
;         const bf16_t* Ga = (br < 2 ? G0 + (size_t)br * M * D : G2) + base;
;         const bf16_t* Gb = (br == 0 ? G0 + (size_t)M * D : G2) + base;
;         bf16_t* O = MRG + base;
; #pragma unroll
;         for (int ai = 0; ai < 2; ++ai) {
;             u32x4 ga[4][2], gb[4][2];
; #pragma unroll
;             for (int m = 0; m < 4; ++m)
; #pragma unroll
;                 for (int bj = 0; bj < 2; ++bj) { const size_t o = (size_t)(ai * HALF + m * 16) * D + HALF * bj; ga[m][bj] = *(const u32x4*)(Ga + o); if (br < 2) gb[m][bj] = *(const u32x4*)(Gb + o); }
.LBB0_581:
	s_cmp_eq_u32 s6, 0
	s_cselect_b64 s[64:65], -1, 0
	v_lshl_add_u32 v130, s4, 8, v210
	s_lshl_b32 s2, s2, 8
	v_ashrrev_i32_e32 v131, 31, v130
	s_ashr_i32 s3, s2, 31
	v_lshlrev_b64 v[130:131], 10, v[130:131]
	s_cmp_gt_i32 s6, 1
	v_lshl_add_u64 v[196:197], v[130:131], 0, s[2:3]
	s_cselect_b64 s[2:3], -1, 0
	s_ashr_i32 s7, s6, 31
	s_lshl_b64 s[4:5], s[6:7], 25
	s_add_u32 s7, s60, s4
	s_addc_u32 s11, s61, s5
	s_cmp_lt_i32 s6, 2
	s_cselect_b64 s[20:21], -1, 0
	v_or_b32_e32 v196, v196, v194
	s_and_b64 s[4:5], s[20:21], exec
	s_cselect_b32 s5, s11, s84
	s_cselect_b32 s4, s7, s47
	v_lshlrev_b64 v[130:131], 1, v[196:197]
	v_lshl_add_u64 v[200:201], s[4:5], 0, v[130:131]
	global_load_dwordx4 v[190:193], v[200:201], off nt
	s_cmp_eq_u32 s6, 0
	s_cselect_b32 s5, s39, s84
	s_cselect_b32 s4, s38, s47
	v_lshl_add_u64 v[198:199], s[4:5], 0, v[130:131]
	s_and_b64 vcc, exec, s[2:3]
	s_cbranch_vccnz .LBB0_583
	global_load_dwordx4 v[158:161], v[198:199], off

;     __device__ __forceinline__ void operator()(acc_t& acc, const Unit& u, int wr, int wc, int fr, int fq) const {
;     ...
;             u32x4 ga[4][2], gb[4][2];
; #pragma unroll
;             for (int m = 0; m < 4; ++m)
; #pragma unroll
;                 for (int bj = 0; bj < 2; ++bj) { const size_t o = (size_t)(ai * HALF + m * 16) * D + HALF * bj; ga[m][bj] = *(const u32x4*)(Ga + o); if (br < 2) gb[m][bj] = *(const u32x4*)(Gb + o); }
.LBB0_597:
	s_and_b64 vcc, exec, s[64:65]
	s_cbranch_vccz .Lp3_skipB
	v_add_co_u32_e32 v244, vcc, 0x40000, v200
	s_nop 1
	v_addc_co_u32_e32 v245, vcc, 0, v201, vcc
	global_load_dwordx4 v[220:223], v[244:245], off nt
	v_add_co_u32_e32 v244, vcc, 0x40000, v200
	s_nop 1
	v_addc_co_u32_e32 v245, vcc, 0, v201, vcc
	global_load_dwordx4 v[224:227], v[244:245], off offset:256 nt
	v_add_co_u32_e32 v244, vcc, 0x48000, v200
	s_nop 1
	v_addc_co_u32_e32 v245, vcc, 0, v201, vcc
	global_load_dwordx4 v[228:231], v[244:245], off nt
	v_add_co_u32_e32 v244, vcc, 0x48000, v200
	s_nop 1
	v_addc_co_u32_e32 v245, vcc, 0, v201, vcc
	global_load_dwordx4 v[232:235], v[244:245], off offset:256 nt
	v_add_co_u32_e32 v244, vcc, 0x50000, v200
	s_nop 1
	v_addc_co_u32_e32 v245, vcc, 0, v201, vcc
	global_load_dwordx4 v[236:239], v[244:245], off nt
	v_add_co_u32_e32 v244, vcc, 0x50000, v200
	s_nop 1
	v_addc_co_u32_e32 v245, vcc, 0, v201, vcc
	global_load_dwordx4 v[240:243], v[244:245], off offset:256 nt
.Lp3_skipB:
	s_and_b64 vcc, exec, s[64:65]
	s_cbranch_vccnz .Lp3w0_a
	s_waitcnt vmcnt(7)
	s_branch .Lp3w0_b

; __device__ __forceinline__ float clampg(unsigned bits) { return __uint_as_float(bits > 0x0da24260u ? bits : 0x0da24260u); }
;     __device__ __forceinline__ void operator()(acc_t& acc, const Unit& u, int wr, int wc, int fr, int fq) const {
;     ...
;                     const u32x4 a = ga[m][bj]; float f[8] = {clampg(a.x << 16), clampg(a.x & 0xffff0000u), clampg(a.y << 16), clampg(a.y & 0xffff0000u), clampg(a.z << 16), clampg(a.z & 0xffff0000u), clampg(a.w << 16), clampg(a.w & 0xffff0000u)};
;                     if (br < 2) { const u32x4 b = gb[m][bj]; const float d[8] = {clampg(b.x << 16), clampg(b.x & 0xffff0000u), clampg(b.y << 16), clampg(b.y & 0xffff0000u), clampg(b.z << 16), clampg(b.z & 0xffff0000u), clampg(b.w << 16), clampg(b.w & 0xffff0000u)};
.Lp3w0_b:
	v_lshlrev_b32_e32 v202, 16, v190
	v_and_b32_e32 v190, 0xffff0000, v190
	v_max_u32_e32 v205, 0xda24260, v190
	v_lshlrev_b32_e32 v190, 16, v191
	v_max_u32_e32 v204, 0xda24260, v202
	v_max_u32_e32 v202, 0xda24260, v190
	v_and_b32_e32 v190, 0xffff0000, v191
	v_max_u32_e32 v203, 0xda24260, v190
	v_lshlrev_b32_e32 v190, 16, v192
	v_max_u32_e32 v206, 0xda24260, v190
	v_and_b32_e32 v190, 0xffff0000, v192
	v_max_u32_e32 v207, 0xda24260, v190
	v_lshlrev_b32_e32 v190, 16, v193
	v_and_b32_e32 v191, 0xffff0000, v193
	v_cndmask_b32_e64 v192, 0, 1, s[2:3]
	v_max_u32_e32 v190, 0xda24260, v190
	v_max_u32_e32 v191, 0xda24260, v191
	v_cmp_ne_u32_e64 s[6:7], 1, v192
	s_andn2_b64 vcc, exec, s[2:3]
	s_mov_b64 s[2:3], -1
	s_cbranch_vccnz .LBB0_599
	s_mov_b64 s[2:3], 0

; __device__ __forceinline__ float clampg(unsigned bits) { return __uint_as_float(bits > 0x0da24260u ? bits : 0x0da24260u); }
;     __device__ __forceinline__ void operator()(acc_t& acc, const Unit& u, int wr, int wc, int fr, int fq) const {
;     ...
;                 for (int bj = 0; bj < 2; ++bj) { const size_t o = (size_t)(ai * HALF + m * 16) * D + HALF * bj; ga[m][bj] = *(const u32x4*)(Ga + o); if (br < 2) gb[m][bj] = *(const u32x4*)(Gb + o); }
; #pragma unroll
;             for (int m = 0; m < 4; ++m)
; #pragma unroll
;                 for (int bj = 0; bj < 2; ++bj) {
;                     const u32x4 a = ga[m][bj]; float f[8] = {clampg(a.x << 16), clampg(a.x & 0xffff0000u), clampg(a.y << 16), clampg(a.y & 0xffff0000u), clampg(a.z << 16), clampg(a.z & 0xffff0000u), clampg(a.w << 16), clampg(a.w & 0xffff0000u)};
.LBB0_646:
	s_and_b64 vcc, exec, s[64:65]
	s_cbranch_vccnz .Lp3w7_a
	s_waitcnt vmcnt(6)
	s_branch .Lp3w7_b

; __device__ __forceinline__ float clampg(unsigned bits) { return __uint_as_float(bits > 0x0da24260u ? bits : 0x0da24260u); }
;     __device__ __forceinline__ void operator()(acc_t& acc, const Unit& u, int wr, int wc, int fr, int fq) const {
;     ...
;                     const u32x4 a = ga[m][bj]; float f[8] = {clampg(a.x << 16), clampg(a.x & 0xffff0000u), clampg(a.y << 16), clampg(a.y & 0xffff0000u), clampg(a.z << 16), clampg(a.z & 0xffff0000u), clampg(a.w << 16), clampg(a.w & 0xffff0000u)};
;                     if (br < 2) { const u32x4 b = gb[m][bj]; const float d[8] = {clampg(b.x << 16), clampg(b.x & 0xffff0000u), clampg(b.y << 16), clampg(b.y & 0xffff0000u), clampg(b.z << 16), clampg(b.z & 0xffff0000u), clampg(b.w << 16), clampg(b.w & 0xffff0000u)};
; #pragma unroll
;                         for (int e = 0; e < 8; ++e) f[e] *= __builtin_amdgcn_rcpf(d[e]); }
;                     f32x4 x0 = acc[ai][bj][m][0], x1 = acc[ai][bj][m][1];
;                     x0[0] *= f[0]; x0[1] *= f[1]; x0[2] *= f[2]; x0[3] *= f[3]; x1[0] *= f[4]; x1[1] *= f[5]; x1[2] *= f[6]; x1[3] *= f[7];
;                     if (br < 2) { acc[ai][bj][m][0] = x0; acc[ai][bj][m][1] = x1; }
.Lp3t_7:
.LBB0_669:
	s_waitcnt vmcnt(7)
	v_lshlrev_b32_e32 v198, 16, v220
	v_and_b32_e32 v190, 0xffff0000, v220
	v_max_u32_e32 v201, 0xda24260, v190
	v_lshlrev_b32_e32 v190, 16, v221
	v_max_u32_e32 v200, 0xda24260, v198
	v_max_u32_e32 v198, 0xda24260, v190
	v_and_b32_e32 v190, 0xffff0000, v221
	v_max_u32_e32 v199, 0xda24260, v190
	v_lshlrev_b32_e32 v190, 16, v222
	v_max_u32_e32 v202, 0xda24260, v190
	v_and_b32_e32 v190, 0xffff0000, v222
	v_max_u32_e32 v203, 0xda24260, v190
	v_lshlrev_b32_e32 v190, 16, v223
	v_and_b32_e32 v191, 0xffff0000, v223
	v_mov_b32_e32 v220, v158
	v_mov_b32_e32 v221, v159
	v_mov_b32_e32 v222, v160
	v_mov_b32_e32 v223, v161
	v_max_u32_e32 v190, 0xda24260, v190
	v_max_u32_e32 v191, 0xda24260, v191
	s_and_b64 vcc, exec, s[6:7]
	s_mov_b64 s[2:3], -1
	s_cbranch_vccnz .LBB0_671
	s_mov_b64 s[2:3], 0

; __device__ __forceinline__ float clampg(unsigned bits) { return __uint_as_float(bits > 0x0da24260u ? bits : 0x0da24260u); }
;     __device__ __forceinline__ void operator()(acc_t& acc, const Unit& u, int wr, int wc, int fr, int fq) const {
;     ...
;                     const u32x4 a = ga[m][bj]; float f[8] = {clampg(a.x << 16), clampg(a.x & 0xffff0000u), clampg(a.y << 16), clampg(a.y & 0xffff0000u), clampg(a.z << 16), clampg(a.z & 0xffff0000u), clampg(a.w << 16), clampg(a.w & 0xffff0000u)};
;                     if (br < 2) { const u32x4 b = gb[m][bj]; const float d[8] = {clampg(b.x << 16), clampg(b.x & 0xffff0000u), clampg(b.y << 16), clampg(b.y & 0xffff0000u), clampg(b.z << 16), clampg(b.z & 0xffff0000u), clampg(b.w << 16), clampg(b.w & 0xffff0000u)};
; #pragma unroll
;                         for (int e = 0; e < 8; ++e) f[e] *= __builtin_amdgcn_rcpf(d[e]); }
;                     f32x4 x0 = acc[ai][bj][m][0], x1 = acc[ai][bj][m][1];
;                     x0[0] *= f[0]; x0[1] *= f[1]; x0[2] *= f[2]; x0[3] *= f[3]; x1[0] *= f[4]; x1[1] *= f[5]; x1[2] *= f[6]; x1[3] *= f[7];
;                     if (br < 2) { acc[ai][bj][m][0] = x0; acc[ai][bj][m][1] = x1; }
.LBB0_676:
	s_waitcnt vmcnt(6)
	v_lshlrev_b32_e32 v158, 16, v224
	v_max_u32_e32 v190, 0xda24260, v158
	v_and_b32_e32 v158, 0xffff0000, v224
	v_max_u32_e32 v191, 0xda24260, v158
	v_lshlrev_b32_e32 v158, 16, v225
	v_max_u32_e32 v160, 0xda24260, v158
	v_and_b32_e32 v158, 0xffff0000, v225
	v_max_u32_e32 v161, 0xda24260, v158
	v_lshlrev_b32_e32 v158, 16, v226
	v_max_u32_e32 v186, 0xda24260, v158
	v_and_b32_e32 v158, 0xffff0000, v226
	v_max_u32_e32 v187, 0xda24260, v158
	v_lshlrev_b32_e32 v158, 16, v227
	v_and_b32_e32 v159, 0xffff0000, v227
	v_mov_b32_e32 v224, v154
	v_mov_b32_e32 v225, v155
	v_mov_b32_e32 v226, v156
	v_mov_b32_e32 v227, v157
	v_max_u32_e32 v158, 0xda24260, v158
	v_max_u32_e32 v159, 0xda24260, v159
	s_and_b64 vcc, exec, s[6:7]
	s_mov_b64 s[2:3], -1
	s_cbranch_vccnz .LBB0_678
	s_mov_b64 s[2:3], 0

; __device__ __forceinline__ float clampg(unsigned bits) { return __uint_as_float(bits > 0x0da24260u ? bits : 0x0da24260u); }
;     __device__ __forceinline__ void operator()(acc_t& acc, const Unit& u, int wr, int wc, int fr, int fq) const {
;     ...
;                     const u32x4 a = ga[m][bj]; float f[8] = {clampg(a.x << 16), clampg(a.x & 0xffff0000u), clampg(a.y << 16), clampg(a.y & 0xffff0000u), clampg(a.z << 16), clampg(a.z & 0xffff0000u), clampg(a.w << 16), clampg(a.w & 0xffff0000u)};
;                     if (br < 2) { const u32x4 b = gb[m][bj]; const float d[8] = {clampg(b.x << 16), clampg(b.x & 0xffff0000u), clampg(b.y << 16), clampg(b.y & 0xffff0000u), clampg(b.z << 16), clampg(b.z & 0xffff0000u), clampg(b.w << 16), clampg(b.w & 0xffff0000u)};
; #pragma unroll
;                         for (int e = 0; e < 8; ++e) f[e] *= __builtin_amdgcn_rcpf(d[e]); }
;                     f32x4 x0 = acc[ai][bj][m][0], x1 = acc[ai][bj][m][1];
;                     x0[0] *= f[0]; x0[1] *= f[1]; x0[2] *= f[2]; x0[3] *= f[3]; x1[0] *= f[4]; x1[1] *= f[5]; x1[2] *= f[6]; x1[3] *= f[7];
;                     if (br < 2) { acc[ai][bj][m][0] = x0; acc[ai][bj][m][1] = x1; }
.LBB0_683:
	s_waitcnt vmcnt(5)
	v_lshlrev_b32_e32 v154, 16, v228
	v_max_u32_e32 v158, 0xda24260, v154
	v_and_b32_e32 v154, 0xffff0000, v228
	v_max_u32_e32 v159, 0xda24260, v154
	v_lshlrev_b32_e32 v154, 16, v229
	v_max_u32_e32 v156, 0xda24260, v154
	v_and_b32_e32 v154, 0xffff0000, v229
	v_max_u32_e32 v157, 0xda24260, v154
	v_lshlrev_b32_e32 v154, 16, v230
	v_max_u32_e32 v160, 0xda24260, v154
	v_and_b32_e32 v154, 0xffff0000, v230
	v_max_u32_e32 v161, 0xda24260, v154
	v_lshlrev_b32_e32 v154, 16, v231
	v_and_b32_e32 v155, 0xffff0000, v231
	v_mov_b32_e32 v228, v150
	v_mov_b32_e32 v229, v151
	v_mov_b32_e32 v230, v152
	v_mov_b32_e32 v231, v153
	v_max_u32_e32 v154, 0xda24260, v154
	v_max_u32_e32 v155, 0xda24260, v155
	s_and_b64 vcc, exec, s[6:7]
	s_mov_b64 s[2:3], -1
	s_cbranch_vccnz .LBB0_685
	s_mov_b64 s[2:3], 0

; __device__ __forceinline__ float clampg(unsigned bits) { return __uint_as_float(bits > 0x0da24260u ? bits : 0x0da24260u); }
;     __device__ __forceinline__ void operator()(acc_t& acc, const Unit& u, int wr, int wc, int fr, int fq) const {
;     ...
;                     const u32x4 a = ga[m][bj]; float f[8] = {clampg(a.x << 16), clampg(a.x & 0xffff0000u), clampg(a.y << 16), clampg(a.y & 0xffff0000u), clampg(a.z << 16), clampg(a.z & 0xffff0000u), clampg(a.w << 16), clampg(a.w & 0xffff0000u)};
;                     if (br < 2) { const u32x4 b = gb[m][bj]; const float d[8] = {clampg(b.x << 16), clampg(b.x & 0xffff0000u), clampg(b.y << 16), clampg(b.y & 0xffff0000u), clampg(b.z << 16), clampg(b.z & 0xffff0000u), clampg(b.w << 16), clampg(b.w & 0xffff0000u)};
; #pragma unroll
;                         for (int e = 0; e < 8; ++e) f[e] *= __builtin_amdgcn_rcpf(d[e]); }
;                     f32x4 x0 = acc[ai][bj][m][0], x1 = acc[ai][bj][m][1];
;                     x0[0] *= f[0]; x0[1] *= f[1]; x0[2] *= f[2]; x0[3] *= f[3]; x1[0] *= f[4]; x1[1] *= f[5]; x1[2] *= f[6]; x1[3] *= f[7];
;                     if (br < 2) { acc[ai][bj][m][0] = x0; acc[ai][bj][m][1] = x1; }
.LBB0_690:
	s_waitcnt vmcnt(4)
	v_lshlrev_b32_e32 v150, 16, v232
	v_max_u32_e32 v154, 0xda24260, v150
	v_and_b32_e32 v150, 0xffff0000, v232
	v_max_u32_e32 v155, 0xda24260, v150
	v_lshlrev_b32_e32 v150, 16, v233
	v_max_u32_e32 v152, 0xda24260, v150
	v_and_b32_e32 v150, 0xffff0000, v233
	v_max_u32_e32 v153, 0xda24260, v150
	v_lshlrev_b32_e32 v150, 16, v234
	v_max_u32_e32 v156, 0xda24260, v150
	v_and_b32_e32 v150, 0xffff0000, v234
	v_max_u32_e32 v157, 0xda24260, v150
	v_lshlrev_b32_e32 v150, 16, v235
	v_and_b32_e32 v151, 0xffff0000, v235
	v_mov_b32_e32 v232, v146
	v_mov_b32_e32 v233, v147
	v_mov_b32_e32 v234, v148
	v_mov_b32_e32 v235, v149
	v_max_u32_e32 v150, 0xda24260, v150
	v_max_u32_e32 v151, 0xda24260, v151
	s_and_b64 vcc, exec, s[6:7]
	s_mov_b64 s[2:3], -1
	s_cbranch_vccnz .LBB0_692
	s_mov_b64 s[2:3], 0

; __device__ __forceinline__ float clampg(unsigned bits) { return __uint_as_float(bits > 0x0da24260u ? bits : 0x0da24260u); }
;     __device__ __forceinline__ void operator()(acc_t& acc, const Unit& u, int wr, int wc, int fr, int fq) const {
;     ...
;                     const u32x4 a = ga[m][bj]; float f[8] = {clampg(a.x << 16), clampg(a.x & 0xffff0000u), clampg(a.y << 16), clampg(a.y & 0xffff0000u), clampg(a.z << 16), clampg(a.z & 0xffff0000u), clampg(a.w << 16), clampg(a.w & 0xffff0000u)};
;                     if (br < 2) { const u32x4 b = gb[m][bj]; const float d[8] = {clampg(b.x << 16), clampg(b.x & 0xffff0000u), clampg(b.y << 16), clampg(b.y & 0xffff0000u), clampg(b.z << 16), clampg(b.z & 0xffff0000u), clampg(b.w << 16), clampg(b.w & 0xffff0000u)};
; #pragma unroll
;                         for (int e = 0; e < 8; ++e) f[e] *= __builtin_amdgcn_rcpf(d[e]); }
;                     f32x4 x0 = acc[ai][bj][m][0], x1 = acc[ai][bj][m][1];
;                     x0[0] *= f[0]; x0[1] *= f[1]; x0[2] *= f[2]; x0[3] *= f[3]; x1[0] *= f[4]; x1[1] *= f[5]; x1[2] *= f[6]; x1[3] *= f[7];
;                     if (br < 2) { acc[ai][bj][m][0] = x0; acc[ai][bj][m][1] = x1; }
.LBB0_697:
	s_waitcnt vmcnt(3)
	v_lshlrev_b32_e32 v146, 16, v236
	v_max_u32_e32 v150, 0xda24260, v146
	v_and_b32_e32 v146, 0xffff0000, v236
	v_max_u32_e32 v151, 0xda24260, v146
	v_lshlrev_b32_e32 v146, 16, v237
	v_max_u32_e32 v148, 0xda24260, v146
	v_and_b32_e32 v146, 0xffff0000, v237
	v_max_u32_e32 v149, 0xda24260, v146
	v_lshlrev_b32_e32 v146, 16, v238
	v_max_u32_e32 v152, 0xda24260, v146
	v_and_b32_e32 v146, 0xffff0000, v238
	v_max_u32_e32 v153, 0xda24260, v146
	v_lshlrev_b32_e32 v146, 16, v239
	v_and_b32_e32 v147, 0xffff0000, v239
	v_mov_b32_e32 v236, v142
	v_mov_b32_e32 v237, v143
	v_mov_b32_e32 v238, v144
	v_mov_b32_e32 v239, v145
	v_max_u32_e32 v146, 0xda24260, v146
	v_max_u32_e32 v147, 0xda24260, v147
	s_and_b64 vcc, exec, s[6:7]
	s_mov_b64 s[2:3], -1
	s_cbranch_vccnz .LBB0_699
	s_mov_b64 s[2:3], 0

; __device__ __forceinline__ float clampg(unsigned bits) { return __uint_as_float(bits > 0x0da24260u ? bits : 0x0da24260u); }
;     __device__ __forceinline__ void operator()(acc_t& acc, const Unit& u, int wr, int wc, int fr, int fq) const {
;     ...
;                     const u32x4 a = ga[m][bj]; float f[8] = {clampg(a.x << 16), clampg(a.x & 0xffff0000u), clampg(a.y << 16), clampg(a.y & 0xffff0000u), clampg(a.z << 16), clampg(a.z & 0xffff0000u), clampg(a.w << 16), clampg(a.w & 0xffff0000u)};
;                     if (br < 2) { const u32x4 b = gb[m][bj]; const float d[8] = {clampg(b.x << 16), clampg(b.x & 0xffff0000u), clampg(b.y << 16), clampg(b.y & 0xffff0000u), clampg(b.z << 16), clampg(b.z & 0xffff0000u), clampg(b.w << 16), clampg(b.w & 0xffff0000u)};
; #pragma unroll
;                         for (int e = 0; e < 8; ++e) f[e] *= __builtin_amdgcn_rcpf(d[e]); }
;                     f32x4 x0 = acc[ai][bj][m][0], x1 = acc[ai][bj][m][1];
;                     x0[0] *= f[0]; x0[1] *= f[1]; x0[2] *= f[2]; x0[3] *= f[3]; x1[0] *= f[4]; x1[1] *= f[5]; x1[2] *= f[6]; x1[3] *= f[7];
;                     if (br < 2) { acc[ai][bj][m][0] = x0; acc[ai][bj][m][1] = x1; }
.LBB0_704:
	s_waitcnt vmcnt(2)
	v_lshlrev_b32_e32 v142, 16, v240
	v_max_u32_e32 v146, 0xda24260, v142
	v_and_b32_e32 v142, 0xffff0000, v240
	v_max_u32_e32 v147, 0xda24260, v142
	v_lshlrev_b32_e32 v142, 16, v241
	v_max_u32_e32 v144, 0xda24260, v142
	v_and_b32_e32 v142, 0xffff0000, v241
	v_max_u32_e32 v145, 0xda24260, v142
	v_lshlrev_b32_e32 v142, 16, v242
	v_max_u32_e32 v148, 0xda24260, v142
	v_and_b32_e32 v142, 0xffff0000, v242
	v_max_u32_e32 v149, 0xda24260, v142
	v_lshlrev_b32_e32 v142, 16, v243
	v_and_b32_e32 v143, 0xffff0000, v243
	v_mov_b32_e32 v240, v138
	v_mov_b32_e32 v241, v139
	v_mov_b32_e32 v242, v140
	v_mov_b32_e32 v243, v141
	v_max_u32_e32 v142, 0xda24260, v142
	v_max_u32_e32 v143, 0xda24260, v143
	s_and_b64 vcc, exec, s[6:7]
	s_mov_b64 s[2:3], -1
	s_cbranch_vccnz .LBB0_706
	s_mov_b64 s[2:3], 0
